# non-temporal hints on once-read streams: phase A residual loads, LRU pass3 tile loads, merge-gate loads in the merge epilogue, adaLN weight loads
# speedup vs baseline: 1.0073x; 1.0027x over previous
; __global__ void __launch_bounds__(512, 2) mk_fwd(Args args) {
;     ...
;         for (int it = bid; it < DEPTH * 96; it += G) {
;             const int L = it / 96, cb = it % 96, ksl = tid >> 6, col = cb * 64 + (tid & 63);
;             float a5[5] = {0.f, 0.f, 0.f, 0.f, 0.f};
;             const float* wp = ada_w + (size_t)L * DM * 6144 + col;
;             for (int k = ksl * 256; k < ksl * 256 + 256; ++k) { const float w = wp[(size_t)k * 6144];
; #pragma unroll
;                 for (int r = 0; r < 5; ++r) a5[r] += sil[r * 2048 + k] * w; }
.Lada_kloop:
	global_load_dword v120, v[22:23], off nt
	v_lshl_add_u64 v[22:23], v[22:23], 0, s[24:25]
	global_load_dword v121, v[22:23], off nt
	v_lshl_add_u64 v[22:23], v[22:23], 0, s[24:25]
	global_load_dword v122, v[22:23], off nt
	v_lshl_add_u64 v[22:23], v[22:23], 0, s[24:25]
	global_load_dword v123, v[22:23], off nt
	v_lshl_add_u64 v[22:23], v[22:23], 0, s[24:25]
	global_load_dword v124, v[22:23], off nt
	v_lshl_add_u64 v[22:23], v[22:23], 0, s[24:25]
	global_load_dword v125, v[22:23], off nt
	v_lshl_add_u64 v[22:23], v[22:23], 0, s[24:25]
	global_load_dword v126, v[22:23], off nt
	v_lshl_add_u64 v[22:23], v[22:23], 0, s[24:25]
	global_load_dword v127, v[22:23], off nt
	v_lshl_add_u64 v[22:23], v[22:23], 0, s[24:25]
	global_load_dword v128, v[22:23], off nt
	v_lshl_add_u64 v[22:23], v[22:23], 0, s[24:25]
	global_load_dword v129, v[22:23], off nt
	v_lshl_add_u64 v[22:23], v[22:23], 0, s[24:25]
	global_load_dword v130, v[22:23], off nt
	v_lshl_add_u64 v[22:23], v[22:23], 0, s[24:25]
	global_load_dword v131, v[22:23], off nt
	v_lshl_add_u64 v[22:23], v[22:23], 0, s[24:25]
	global_load_dword v132, v[22:23], off nt
	v_lshl_add_u64 v[22:23], v[22:23], 0, s[24:25]
	global_load_dword v133, v[22:23], off nt
	v_lshl_add_u64 v[22:23], v[22:23], 0, s[24:25]
	global_load_dword v134, v[22:23], off nt
	v_lshl_add_u64 v[22:23], v[22:23], 0, s[24:25]
	global_load_dword v135, v[22:23], off nt
	v_lshl_add_u64 v[22:23], v[22:23], 0, s[24:25]
	global_load_dword v136, v[22:23], off nt
	v_lshl_add_u64 v[22:23], v[22:23], 0, s[24:25]
	global_load_dword v137, v[22:23], off nt
	v_lshl_add_u64 v[22:23], v[22:23], 0, s[24:25]
	global_load_dword v138, v[22:23], off nt
	v_lshl_add_u64 v[22:23], v[22:23], 0, s[24:25]
	global_load_dword v139, v[22:23], off nt
	v_lshl_add_u64 v[22:23], v[22:23], 0, s[24:25]
	global_load_dword v140, v[22:23], off nt
	v_lshl_add_u64 v[22:23], v[22:23], 0, s[24:25]
	global_load_dword v141, v[22:23], off nt
	v_lshl_add_u64 v[22:23], v[22:23], 0, s[24:25]
	global_load_dword v142, v[22:23], off nt
	v_lshl_add_u64 v[22:23], v[22:23], 0, s[24:25]
	global_load_dword v143, v[22:23], off nt
	v_lshl_add_u64 v[22:23], v[22:23], 0, s[24:25]
	global_load_dword v144, v[22:23], off nt
	v_lshl_add_u64 v[22:23], v[22:23], 0, s[24:25]
	global_load_dword v145, v[22:23], off nt
	v_lshl_add_u64 v[22:23], v[22:23], 0, s[24:25]
	global_load_dword v146, v[22:23], off nt
	v_lshl_add_u64 v[22:23], v[22:23], 0, s[24:25]
	global_load_dword v147, v[22:23], off nt
	v_lshl_add_u64 v[22:23], v[22:23], 0, s[24:25]
	global_load_dword v148, v[22:23], off nt
	v_lshl_add_u64 v[22:23], v[22:23], 0, s[24:25]
	global_load_dword v149, v[22:23], off nt
	v_lshl_add_u64 v[22:23], v[22:23], 0, s[24:25]
	global_load_dword v150, v[22:23], off nt
	v_lshl_add_u64 v[22:23], v[22:23], 0, s[24:25]
	global_load_dword v151, v[22:23], off nt
	v_lshl_add_u64 v[22:23], v[22:23], 0, s[24:25]
	v_add_u32_e32 v21, s13, v9
	v_add_u32_e32 v24, 0x11000, v21
	ds_read_b128 v[160:163], v24
	ds_read_b128 v[164:167], v24 offset:8192
	ds_read_b128 v[168:171], v24 offset:16384
	ds_read_b128 v[172:175], v24 offset:24576
	ds_read_b128 v[176:179], v24 offset:32768
	s_waitcnt vmcnt(28) lgkmcnt(0)
	v_fmac_f32_e32 v14, v120, v160
	v_fmac_f32_e32 v15, v120, v164
	v_fmac_f32_e32 v16, v120, v168
	v_fmac_f32_e32 v17, v120, v172
	v_fmac_f32_e32 v20, v120, v176
	v_fmac_f32_e32 v14, v121, v161
	v_fmac_f32_e32 v15, v121, v165
	v_fmac_f32_e32 v16, v121, v169
	v_fmac_f32_e32 v17, v121, v173
	v_fmac_f32_e32 v20, v121, v177
	v_fmac_f32_e32 v14, v122, v162
	v_fmac_f32_e32 v15, v122, v166
	v_fmac_f32_e32 v16, v122, v170
	v_fmac_f32_e32 v17, v122, v174
	v_fmac_f32_e32 v20, v122, v178
	v_fmac_f32_e32 v14, v123, v163
	v_fmac_f32_e32 v15, v123, v167
	v_fmac_f32_e32 v16, v123, v171
	v_fmac_f32_e32 v17, v123, v175
	v_fmac_f32_e32 v20, v123, v179
	ds_read_b128 v[160:163], v24 offset:16
	ds_read_b128 v[164:167], v24 offset:8208
	ds_read_b128 v[168:171], v24 offset:16400
	ds_read_b128 v[172:175], v24 offset:24592
	ds_read_b128 v[176:179], v24 offset:32784
	s_waitcnt vmcnt(24) lgkmcnt(0)
	v_fmac_f32_e32 v14, v124, v160
	v_fmac_f32_e32 v15, v124, v164
	v_fmac_f32_e32 v16, v124, v168
	v_fmac_f32_e32 v17, v124, v172
	v_fmac_f32_e32 v20, v124, v176
	v_fmac_f32_e32 v14, v125, v161
	v_fmac_f32_e32 v15, v125, v165
	v_fmac_f32_e32 v16, v125, v169
	v_fmac_f32_e32 v17, v125, v173
	v_fmac_f32_e32 v20, v125, v177
	v_fmac_f32_e32 v14, v126, v162
	v_fmac_f32_e32 v15, v126, v166
	v_fmac_f32_e32 v16, v126, v170
	v_fmac_f32_e32 v17, v126, v174
	v_fmac_f32_e32 v20, v126, v178
	v_fmac_f32_e32 v14, v127, v163
	v_fmac_f32_e32 v15, v127, v167
	v_fmac_f32_e32 v16, v127, v171
	v_fmac_f32_e32 v17, v127, v175
	v_fmac_f32_e32 v20, v127, v179
	ds_read_b128 v[160:163], v24 offset:32
	ds_read_b128 v[164:167], v24 offset:8224
	ds_read_b128 v[168:171], v24 offset:16416
	ds_read_b128 v[172:175], v24 offset:24608
	ds_read_b128 v[176:179], v24 offset:32800
	s_waitcnt vmcnt(20) lgkmcnt(0)
	v_fmac_f32_e32 v14, v128, v160
	v_fmac_f32_e32 v15, v128, v164
	v_fmac_f32_e32 v16, v128, v168
	v_fmac_f32_e32 v17, v128, v172
	v_fmac_f32_e32 v20, v128, v176
	v_fmac_f32_e32 v14, v129, v161
	v_fmac_f32_e32 v15, v129, v165
	v_fmac_f32_e32 v16, v129, v169
	v_fmac_f32_e32 v17, v129, v173
	v_fmac_f32_e32 v20, v129, v177
	v_fmac_f32_e32 v14, v130, v162
	v_fmac_f32_e32 v15, v130, v166
	v_fmac_f32_e32 v16, v130, v170
	v_fmac_f32_e32 v17, v130, v174
	v_fmac_f32_e32 v20, v130, v178
	v_fmac_f32_e32 v14, v131, v163
	v_fmac_f32_e32 v15, v131, v167
	v_fmac_f32_e32 v16, v131, v171
	v_fmac_f32_e32 v17, v131, v175
	v_fmac_f32_e32 v20, v131, v179
	ds_read_b128 v[160:163], v24 offset:48
	ds_read_b128 v[164:167], v24 offset:8240
	ds_read_b128 v[168:171], v24 offset:16432
	ds_read_b128 v[172:175], v24 offset:24624
	ds_read_b128 v[176:179], v24 offset:32816
	s_waitcnt vmcnt(16) lgkmcnt(0)
; __global__ void __launch_bounds__(512, 2) mk_fwd(Args args) {
;     ...
;             for (int k = ksl * 256; k < ksl * 256 + 256; ++k) { const float w = wp[(size_t)k * 6144];
; #pragma unroll
;                 for (int r = 0; r < 5; ++r) a5[r] += sil[r * 2048 + k] * w; }
; #pragma unroll
;             for (int r = 0; r < 5; ++r) red[(ksl * 5 + r) * 64 + (tid & 63)] = a5[r];
;             __syncthreads();
;             if (tid < 320) { const int r = tid >> 6, cc = tid & 63; float s = 0.f;
; #pragma unroll
;                 for (int k = 0; k < 8; ++k) s += red[(k * 5 + r) * 64 + cc];
;                 MOD[((size_t)L * 5 + r) * 6144 + cb * 64 + cc] = s + ada_b[(size_t)L * 6144 + cb * 64 + cc]; }
;             __syncthreads();
	v_fmac_f32_e32 v14, v132, v160
	v_fmac_f32_e32 v15, v132, v164
	v_fmac_f32_e32 v16, v132, v168
	v_fmac_f32_e32 v17, v132, v172
	v_fmac_f32_e32 v20, v132, v176
	v_fmac_f32_e32 v14, v133, v161
	v_fmac_f32_e32 v15, v133, v165
	v_fmac_f32_e32 v16, v133, v169
	v_fmac_f32_e32 v17, v133, v173
	v_fmac_f32_e32 v20, v133, v177
	v_fmac_f32_e32 v14, v134, v162
	v_fmac_f32_e32 v15, v134, v166
	v_fmac_f32_e32 v16, v134, v170
	v_fmac_f32_e32 v17, v134, v174
	v_fmac_f32_e32 v20, v134, v178
	v_fmac_f32_e32 v14, v135, v163
	v_fmac_f32_e32 v15, v135, v167
	v_fmac_f32_e32 v16, v135, v171
	v_fmac_f32_e32 v17, v135, v175
	v_fmac_f32_e32 v20, v135, v179
	ds_read_b128 v[160:163], v24 offset:64
	ds_read_b128 v[164:167], v24 offset:8256
	ds_read_b128 v[168:171], v24 offset:16448
	ds_read_b128 v[172:175], v24 offset:24640
	ds_read_b128 v[176:179], v24 offset:32832
	s_waitcnt vmcnt(12) lgkmcnt(0)
	v_fmac_f32_e32 v14, v136, v160
	v_fmac_f32_e32 v15, v136, v164
	v_fmac_f32_e32 v16, v136, v168
	v_fmac_f32_e32 v17, v136, v172
	v_fmac_f32_e32 v20, v136, v176
	v_fmac_f32_e32 v14, v137, v161
	v_fmac_f32_e32 v15, v137, v165
	v_fmac_f32_e32 v16, v137, v169
	v_fmac_f32_e32 v17, v137, v173
	v_fmac_f32_e32 v20, v137, v177
	v_fmac_f32_e32 v14, v138, v162
	v_fmac_f32_e32 v15, v138, v166
	v_fmac_f32_e32 v16, v138, v170
	v_fmac_f32_e32 v17, v138, v174
	v_fmac_f32_e32 v20, v138, v178
	v_fmac_f32_e32 v14, v139, v163
	v_fmac_f32_e32 v15, v139, v167
	v_fmac_f32_e32 v16, v139, v171
	v_fmac_f32_e32 v17, v139, v175
	v_fmac_f32_e32 v20, v139, v179
	ds_read_b128 v[160:163], v24 offset:80
	ds_read_b128 v[164:167], v24 offset:8272
	ds_read_b128 v[168:171], v24 offset:16464
	ds_read_b128 v[172:175], v24 offset:24656
	ds_read_b128 v[176:179], v24 offset:32848
	s_waitcnt vmcnt(8) lgkmcnt(0)
	v_fmac_f32_e32 v14, v140, v160
	v_fmac_f32_e32 v15, v140, v164
	v_fmac_f32_e32 v16, v140, v168
	v_fmac_f32_e32 v17, v140, v172
	v_fmac_f32_e32 v20, v140, v176
	v_fmac_f32_e32 v14, v141, v161
	v_fmac_f32_e32 v15, v141, v165
	v_fmac_f32_e32 v16, v141, v169
	v_fmac_f32_e32 v17, v141, v173
	v_fmac_f32_e32 v20, v141, v177
	v_fmac_f32_e32 v14, v142, v162
	v_fmac_f32_e32 v15, v142, v166
	v_fmac_f32_e32 v16, v142, v170
	v_fmac_f32_e32 v17, v142, v174
	v_fmac_f32_e32 v20, v142, v178
	v_fmac_f32_e32 v14, v143, v163
	v_fmac_f32_e32 v15, v143, v167
	v_fmac_f32_e32 v16, v143, v171
	v_fmac_f32_e32 v17, v143, v175
	v_fmac_f32_e32 v20, v143, v179
	ds_read_b128 v[160:163], v24 offset:96
	ds_read_b128 v[164:167], v24 offset:8288
	ds_read_b128 v[168:171], v24 offset:16480
	ds_read_b128 v[172:175], v24 offset:24672
	ds_read_b128 v[176:179], v24 offset:32864
	s_waitcnt vmcnt(4) lgkmcnt(0)
	v_fmac_f32_e32 v14, v144, v160
	v_fmac_f32_e32 v15, v144, v164
	v_fmac_f32_e32 v16, v144, v168
	v_fmac_f32_e32 v17, v144, v172
	v_fmac_f32_e32 v20, v144, v176
	v_fmac_f32_e32 v14, v145, v161
	v_fmac_f32_e32 v15, v145, v165
	v_fmac_f32_e32 v16, v145, v169
	v_fmac_f32_e32 v17, v145, v173
	v_fmac_f32_e32 v20, v145, v177
	v_fmac_f32_e32 v14, v146, v162
	v_fmac_f32_e32 v15, v146, v166
	v_fmac_f32_e32 v16, v146, v170
	v_fmac_f32_e32 v17, v146, v174
	v_fmac_f32_e32 v20, v146, v178
	v_fmac_f32_e32 v14, v147, v163
	v_fmac_f32_e32 v15, v147, v167
	v_fmac_f32_e32 v16, v147, v171
	v_fmac_f32_e32 v17, v147, v175
	v_fmac_f32_e32 v20, v147, v179
	ds_read_b128 v[160:163], v24 offset:112
	ds_read_b128 v[164:167], v24 offset:8304
	ds_read_b128 v[168:171], v24 offset:16496
	ds_read_b128 v[172:175], v24 offset:24688
	ds_read_b128 v[176:179], v24 offset:32880
	s_waitcnt vmcnt(0) lgkmcnt(0)
	v_fmac_f32_e32 v14, v148, v160
	v_fmac_f32_e32 v15, v148, v164
	v_fmac_f32_e32 v16, v148, v168
	v_fmac_f32_e32 v17, v148, v172
	v_fmac_f32_e32 v20, v148, v176
	v_fmac_f32_e32 v14, v149, v161
	v_fmac_f32_e32 v15, v149, v165
	v_fmac_f32_e32 v16, v149, v169
	v_fmac_f32_e32 v17, v149, v173
	v_fmac_f32_e32 v20, v149, v177
	v_fmac_f32_e32 v14, v150, v162
	v_fmac_f32_e32 v15, v150, v166
	v_fmac_f32_e32 v16, v150, v170
	v_fmac_f32_e32 v17, v150, v174
	v_fmac_f32_e32 v20, v150, v178
	v_fmac_f32_e32 v14, v151, v163
	v_fmac_f32_e32 v15, v151, v167
	v_fmac_f32_e32 v16, v151, v171
	v_fmac_f32_e32 v17, v151, v175
	v_fmac_f32_e32 v20, v151, v179
	s_add_i32 s13, s13, 128
	s_cmpk_eq_i32 s13, 0x400
	s_cbranch_scc0 .Lada_kloop
	ds_write2st64_b32 v19, v14, v15 offset1:1
	ds_write2st64_b32 v19, v16, v17 offset0:2 offset1:3
	ds_write_b32 v19, v20 offset:1024
	s_waitcnt lgkmcnt(0)
	s_barrier
	s_and_saveexec_b64 s[0:1], s[2:3]
	s_cbranch_execz .LBB0_89
	s_ashr_i32 s13, s12, 31
	s_mul_i32 s23, s18, 0x6000
	s_mul_hi_i32 s19, s18, 0x6000
	s_add_u32 s23, s50, s23
	s_addc_u32 s19, s51, s19
	s_lshl_b64 s[12:13], s[12:13], 2
	s_add_u32 s24, s23, s12
	s_addc_u32 s25, s19, s13
	global_load_dword v26, v2, s[24:25]
	v_add_u32_e32 v24, v7, v1
	v_mad_i64_i32 v[12:13], s[18:19], s18, 5, v[10:11]
	v_mov_b64_e32 v[14:15], s[4:5]
	ds_read2st64_b32 v[16:17], v24 offset1:5
	ds_read2st64_b32 v[20:21], v24 offset0:10 offset1:15
	ds_read2st64_b32 v[22:23], v24 offset0:20 offset1:25
	ds_read2st64_b32 v[24:25], v24 offset0:30 offset1:35
	v_mad_u64_u32 v[14:15], s[18:19], v12, s14, v[14:15]
	v_mad_i32_i24 v15, v13, s14, v15
	v_lshl_add_u64 v[12:13], v[14:15], 0, s[12:13]
	s_waitcnt lgkmcnt(3)
	v_add_f32_e32 v14, 0, v16
	v_add_f32_e32 v14, v14, v17
	s_waitcnt lgkmcnt(2)
	v_add_f32_e32 v14, v14, v20
	v_add_f32_e32 v14, v14, v21
	s_waitcnt lgkmcnt(1)
	v_add_f32_e32 v14, v14, v22
	v_add_f32_e32 v14, v14, v23
	s_waitcnt lgkmcnt(0)
	v_add_f32_e32 v14, v14, v24
	v_add_f32_e32 v14, v14, v25
	v_lshl_add_u64 v[12:13], v[12:13], 0, v[2:3]
	s_waitcnt vmcnt(0)
	v_add_f32_e32 v14, v14, v26
	global_store_dword v[12:13], v14, off
	s_branch .LBB0_89

; __device__ __forceinline__ unsigned cvt_pk(float lo, float hi) { f32x2_t v = {lo, hi}; bf16x2_t b = __builtin_convertvector(v, bf16x2_t); return __builtin_bit_cast(unsigned, b); }
; __global__ void __launch_bounds__(512, 2) mk_fwd(Args args) {
;     ...
;         for (int row = gw; row < MROWS; row += NGW) {
;             const bool lat = row < NLAT;
;             const float* src = (layer == 0) ? (lat ? x_in + (size_t)row * DM : ctx_in + (size_t)(row - NLAT) * DM) : XCUR + (size_t)row * DM;
;             const float* mr = MOD + (size_t)layer * 5 * 6144 + (size_t)(lat ? (row >> 12) : 4) * 6144;
;             f32x4 v[8]; float ss = 0.f;
; #pragma unroll
;             for (int jv = 0; jv < 8; ++jv) { v[jv] = *(const f32x4*)(src + 4 * (lane + 64 * jv)); ss += (v[jv][0] * v[jv][0] + v[jv][1] * v[jv][1]) + (v[jv][2] * v[jv][2] + v[jv][3] * v[jv][3]); }
;             const float rinv = rsqrtf(wave_sum(ss, lane) * (1.f / DM) + EPS);
; #pragma unroll
;             for (int jv = 0; jv < 8; ++jv) { const int col = 4 * (lane + 64 * jv);
;                 const f32x4 gg = *(const f32x4*)(norm_g + layer * DM + col), sh = *(const f32x4*)(mr + col), sc = *(const f32x4*)(mr + 2048 + col);
;                 const f32x4 hh = (v[jv] * rinv * gg) * (sc + 1.f) + sh;
;                 u32x2 w; w.x = cvt_pk(hh[0], hh[1]); w.y = cvt_pk(hh[2], hh[3]); *(u32x2*)(HB + (size_t)row * DM + col) = w; }
.LBB0_122:
	s_min_i32 s28, s0, 0x4000
	s_ashr_i32 s28, s28, 12
	s_mul_hi_i32 s29, s28, 0x6000
	s_mulk_i32 s28, 0x6000
	s_add_u32 s28, s18, s28
	s_addc_u32 s29, s19, s29
	s_add_u32 s30, s28, 0x2000
	s_addc_u32 s31, s29, 0
	global_load_dwordx4 v[104:107], v[32:33], off
	global_load_dwordx4 v[108:111], v[32:33], off offset:1024
	global_load_dwordx4 v[112:115], v[32:33], off offset:2048
	global_load_dwordx4 v[116:119], v[32:33], off offset:3072
	global_load_dwordx4 v[120:123], v[34:35], off
	global_load_dwordx4 v[124:127], v[36:37], off
	global_load_dwordx4 v[128:131], v[38:39], off
	global_load_dwordx4 v[132:135], v[40:41], off
	global_load_dwordx4 v[136:139], v51, s[28:29]
	global_load_dwordx4 v[140:143], v51, s[28:29] offset:1024
	global_load_dwordx4 v[144:147], v51, s[28:29] offset:2048
	global_load_dwordx4 v[148:151], v51, s[28:29] offset:3072
	global_load_dwordx4 v[152:155], v52, s[28:29]
	global_load_dwordx4 v[156:159], v53, s[28:29]
	global_load_dwordx4 v[160:163], v54, s[28:29]
	global_load_dwordx4 v[164:167], v55, s[28:29]
	global_load_dwordx4 v[168:171], v51, s[30:31]
	global_load_dwordx4 v[172:175], v56, s[30:31]
	global_load_dwordx4 v[176:179], v57, s[30:31]
	global_load_dwordx4 v[180:183], v58, s[30:31]
	global_load_dwordx4 v[184:187], v52, s[30:31]
	global_load_dwordx4 v[188:191], v53, s[30:31]
	global_load_dwordx4 v[200:203], v54, s[30:31]
	global_load_dwordx4 v[204:207], v55, s[30:31]
	global_load_dwordx4 v[28:31], v51, s[10:11] nt
	global_load_dwordx4 v[0:3], v51, s[10:11] offset:1024 nt
	global_load_dwordx4 v[12:15], v51, s[10:11] offset:2048 nt
	global_load_dwordx4 v[208:211], v51, s[10:11] offset:3072 nt
	global_load_dwordx4 v[212:215], v52, s[10:11] nt
	global_load_dwordx4 v[216:219], v53, s[10:11] nt
	global_load_dwordx4 v[220:223], v54, s[10:11] nt
	global_load_dwordx4 v[224:227], v55, s[10:11] nt
	s_min_i32 s12, s0, 0x4000
	s_ashr_i32 s13, s12, 12
	s_mul_hi_i32 s12, s13, 0x6000
	s_mulk_i32 s13, 0x6000
	s_waitcnt vmcnt(7)
	v_mov_b32_e32 v6, v29
	s_waitcnt vmcnt(6)
	v_mov_b32_e32 v7, v1
	v_mov_b32_e32 v4, v28
	v_mov_b32_e32 v5, v0
	v_pk_mul_f32 v[6:7], v[6:7], v[6:7]
	v_mov_b32_e32 v8, v31
	v_mov_b32_e32 v9, v3
	v_pk_fma_f32 v[4:5], v[4:5], v[4:5], v[6:7]
	v_mov_b32_e32 v6, v30
	v_mov_b32_e32 v7, v2
	v_pk_mul_f32 v[8:9], v[8:9], v[8:9]
	s_nop 0
	v_pk_fma_f32 v[6:7], v[6:7], v[6:7], v[8:9]
	s_nop 0
	v_pk_add_f32 v[16:17], v[4:5], v[6:7]
	s_waitcnt vmcnt(5)
	v_pk_mul_f32 v[4:5], v[14:15], v[14:15]
	v_pk_mul_f32 v[6:7], v[12:13], v[12:13]
	v_pk_add_f32 v[16:17], v[16:17], v[16:17] op_sel:[0,1] op_sel_hi:[1,0]
	v_pk_mov_b32 v[8:9], v[6:7], v[4:5] op_sel:[1,0]
	v_mov_b32_e32 v7, v5
	v_pk_add_f32 v[18:19], v[8:9], v[6:7]
	s_waitcnt vmcnt(2)
	v_mov_b64_e32 v[8:9], v[208:209]
	v_mov_b64_e32 v[10:11], v[210:211]
	v_mov_b64_e32 v[4:5], v[212:213]
	v_mov_b64_e32 v[6:7], v[214:215]
	v_mov_b64_e32 v[24:25], v[216:217]
	v_mov_b64_e32 v[26:27], v[218:219]
	v_pk_add_f32 v[18:19], v[18:19], v[18:19] op_sel:[0,1] op_sel_hi:[1,0]
	s_nop 0
	v_mul_f32_e32 v20, v4, v4
	v_mul_f32_e32 v21, v5, v5
	v_mov_b32_e32 v17, v20
	v_mov_b32_e32 v19, v21
	v_pk_add_f32 v[16:17], v[16:17], v[18:19]
	v_mul_f32_e32 v18, v9, v9
	v_mul_f32_e32 v20, v11, v11
	v_mul_f32_e32 v22, v6, v6
	v_mul_f32_e32 v23, v7, v7
	v_pk_fma_f32 v[18:19], v[8:9], v[8:9], v[18:19] op_sel_hi:[1,1,0]
	v_pk_fma_f32 v[20:21], v[10:11], v[10:11], v[20:21] op_sel_hi:[1,1,0]
	v_mov_b32_e32 v19, v22
	v_mov_b32_e32 v21, v23
	v_pk_add_f32 v[18:19], v[18:19], v[20:21]
	s_nop 0
	v_pk_add_f32 v[60:61], v[16:17], v[18:19]
	s_nop 0
	v_pk_mul_f32 v[16:17], v[26:27], v[26:27]
	v_pk_mul_f32 v[18:19], v[24:25], v[24:25]
	v_pk_add_f32 v[60:61], v[60:61], v[60:61] op_sel:[0,1] op_sel_hi:[1,0]
	v_pk_mov_b32 v[20:21], v[18:19], v[16:17] op_sel:[1,0]
	v_mov_b32_e32 v19, v17
	v_pk_add_f32 v[62:63], v[20:21], v[18:19]
	s_waitcnt vmcnt(0)
	v_mov_b64_e32 v[16:17], v[220:221]
	v_mov_b64_e32 v[18:19], v[222:223]
	v_mov_b64_e32 v[20:21], v[224:225]
	v_mov_b64_e32 v[22:23], v[226:227]
	v_pk_add_f32 v[62:63], v[62:63], v[62:63] op_sel:[0,1] op_sel_hi:[1,0]
	s_add_u32 s10, s18, s13
	s_addc_u32 s11, s19, s12
	s_add_u32 s12, s10, 0x2000
	s_addc_u32 s13, s11, 0
	s_lshl_b64 s[14:15], s[14:15], 12
	s_add_u32 s0, s0, s2
	s_addc_u32 s1, s1, s3
	s_add_u32 s6, s6, s8
	s_addc_u32 s7, s7, s9
	s_cmpk_gt_i32 s0, 0x43ff
	s_waitcnt vmcnt(0)
	v_mul_f32_e32 v44, v20, v20
	v_mul_f32_e32 v59, v21, v21
	v_mov_b32_e32 v61, v44
	v_mov_b32_e32 v63, v59
	v_mul_f32_e32 v44, v17, v17
	v_mul_f32_e32 v64, v22, v22
	v_pk_add_f32 v[60:61], v[60:61], v[62:63]
	v_pk_fma_f32 v[62:63], v[16:17], v[16:17], v[44:45] op_sel_hi:[1,1,0]
	v_mul_f32_e32 v44, v19, v19
	v_mul_f32_e32 v66, v23, v23
	v_mov_b32_e32 v63, v64
	v_pk_fma_f32 v[64:65], v[18:19], v[18:19], v[44:45] op_sel_hi:[1,1,0]
	s_nop 0
	v_mov_b32_e32 v65, v66
	v_pk_add_f32 v[62:63], v[62:63], v[64:65]
	s_nop 0
	v_pk_add_f32 v[60:61], v[60:61], v[62:63]
	s_nop 0
	v_add_f32_e32 v44, v60, v61
	s_nop 0
	ds_bpermute_b32 v59, v45, v44
	s_waitcnt lgkmcnt(0)
	v_add_f32_e32 v44, v44, v59
	ds_bpermute_b32 v59, v46, v44
	s_waitcnt lgkmcnt(0)
	v_add_f32_e32 v44, v44, v59
	ds_bpermute_b32 v59, v47, v44
	s_waitcnt lgkmcnt(0)
; __device__ __forceinline__ unsigned cvt_pk(float lo, float hi) { f32x2_t v = {lo, hi}; bf16x2_t b = __builtin_convertvector(v, bf16x2_t); return __builtin_bit_cast(unsigned, b); }
; __global__ void __launch_bounds__(512, 2) mk_fwd(Args args) {
;     ...
;             const float rinv = rsqrtf(wave_sum(ss, lane) * (1.f / DM) + EPS);
; #pragma unroll
;             for (int jv = 0; jv < 8; ++jv) { const int col = 4 * (lane + 64 * jv);
;                 const f32x4 gg = *(const f32x4*)(norm_g + layer * DM + col), sh = *(const f32x4*)(mr + col), sc = *(const f32x4*)(mr + 2048 + col);
;                 const f32x4 hh = (v[jv] * rinv * gg) * (sc + 1.f) + sh;
;                 u32x2 w; w.x = cvt_pk(hh[0], hh[1]); w.y = cvt_pk(hh[2], hh[3]); *(u32x2*)(HB + (size_t)row * DM + col) = w; }
	v_add_f32_e32 v44, v44, v59
	ds_bpermute_b32 v59, v48, v44
	s_waitcnt lgkmcnt(0)
	v_add_f32_e32 v44, v44, v59
	ds_bpermute_b32 v59, v49, v44
	s_waitcnt lgkmcnt(0)
	v_add_f32_e32 v44, v44, v59
	ds_bpermute_b32 v59, v50, v44
	s_waitcnt lgkmcnt(0)
	v_add_f32_e32 v44, v44, v59
	v_fmamk_f32 v44, v44, 0x3a000000, v250
	v_cmp_gt_f32_e32 vcc, s61, v44
	v_mul_f32_e32 v59, 0x4b800000, v44
	s_nop 0
	v_cndmask_b32_e32 v44, v44, v59, vcc
	v_rsq_f32_e32 v44, v44
	s_nop 0
	v_mul_f32_e32 v59, 0x45800000, v44
	v_cndmask_b32_e32 v44, v44, v59, vcc
	v_pk_mul_f32 v[30:31], v[44:45], v[30:31] op_sel_hi:[0,1]
	v_pk_mul_f32 v[28:29], v[44:45], v[28:29] op_sel_hi:[0,1]
	v_pk_mul_f32 v[2:3], v[44:45], v[2:3] op_sel_hi:[0,1]
	v_pk_mul_f32 v[0:1], v[44:45], v[0:1] op_sel_hi:[0,1]
	v_pk_mul_f32 v[14:15], v[44:45], v[14:15] op_sel_hi:[0,1]
	v_pk_mul_f32 v[12:13], v[44:45], v[12:13] op_sel_hi:[0,1]
	v_pk_mul_f32 v[10:11], v[44:45], v[10:11] op_sel_hi:[0,1]
	v_pk_mul_f32 v[8:9], v[44:45], v[8:9] op_sel_hi:[0,1]
	v_pk_mul_f32 v[6:7], v[44:45], v[6:7] op_sel_hi:[0,1]
	v_pk_mul_f32 v[4:5], v[44:45], v[4:5] op_sel_hi:[0,1]
	v_lshl_add_u64 v[84:85], v[42:43], 0, s[14:15]
	v_pk_mul_f32 v[28:29], v[104:105], v[28:29]
	v_pk_mul_f32 v[30:31], v[106:107], v[30:31]
	v_pk_add_f32 v[170:171], v[170:171], 1.0 op_sel_hi:[1,0]
	v_pk_add_f32 v[168:169], v[168:169], 1.0 op_sel_hi:[1,0]
	v_pk_fma_f32 v[30:31], v[170:171], v[30:31], v[138:139]
	v_pk_fma_f32 v[28:29], v[168:169], v[28:29], v[136:137]
	s_nop 0
	v_cvt_pk_bf16_f32 v28, v28, v29
	v_cvt_pk_bf16_f32 v29, v30, v31
	global_store_dwordx2 v[84:85], v[28:29], off
	v_pk_mul_f32 v[0:1], v[108:109], v[0:1]
	v_pk_mul_f32 v[2:3], v[110:111], v[2:3]
	v_pk_add_f32 v[174:175], v[174:175], 1.0 op_sel_hi:[1,0]
	v_pk_add_f32 v[172:173], v[172:173], 1.0 op_sel_hi:[1,0]
	v_pk_fma_f32 v[2:3], v[174:175], v[2:3], v[142:143]
	v_pk_fma_f32 v[0:1], v[172:173], v[0:1], v[140:141]
	s_nop 0
	v_cvt_pk_bf16_f32 v0, v0, v1
	v_cvt_pk_bf16_f32 v1, v2, v3
	global_store_dwordx2 v[84:85], v[0:1], off offset:512
	v_pk_mul_f32 v[12:13], v[112:113], v[12:13]
	v_pk_mul_f32 v[14:15], v[114:115], v[14:15]
	v_pk_add_f32 v[178:179], v[178:179], 1.0 op_sel_hi:[1,0]
	v_pk_add_f32 v[176:177], v[176:177], 1.0 op_sel_hi:[1,0]
	v_pk_fma_f32 v[14:15], v[178:179], v[14:15], v[146:147]
	v_pk_fma_f32 v[12:13], v[176:177], v[12:13], v[144:145]
	s_nop 0
	v_cvt_pk_bf16_f32 v12, v12, v13
	v_cvt_pk_bf16_f32 v13, v14, v15
	global_store_dwordx2 v[84:85], v[12:13], off offset:1024
	v_pk_mul_f32 v[8:9], v[116:117], v[8:9]
	v_pk_mul_f32 v[10:11], v[118:119], v[10:11]
	v_pk_add_f32 v[182:183], v[182:183], 1.0 op_sel_hi:[1,0]
	v_pk_add_f32 v[180:181], v[180:181], 1.0 op_sel_hi:[1,0]
	v_pk_fma_f32 v[10:11], v[182:183], v[10:11], v[150:151]
	v_pk_fma_f32 v[8:9], v[180:181], v[8:9], v[148:149]
	s_nop 0
	v_cvt_pk_bf16_f32 v8, v8, v9
	v_cvt_pk_bf16_f32 v9, v10, v11
	global_store_dwordx2 v[84:85], v[8:9], off offset:1536
	v_pk_mul_f32 v[4:5], v[120:121], v[4:5]
	v_pk_mul_f32 v[6:7], v[122:123], v[6:7]
	v_pk_add_f32 v[186:187], v[186:187], 1.0 op_sel_hi:[1,0]
	v_pk_add_f32 v[184:185], v[184:185], 1.0 op_sel_hi:[1,0]
	v_pk_fma_f32 v[6:7], v[186:187], v[6:7], v[154:155]
	v_pk_fma_f32 v[4:5], v[184:185], v[4:5], v[152:153]
	s_nop 0
	v_cvt_pk_bf16_f32 v4, v4, v5
	v_cvt_pk_bf16_f32 v5, v6, v7
	global_store_dwordx2 v[84:85], v[4:5], off offset:2048
	v_pk_mul_f32 v[24:25], v[44:45], v[24:25] op_sel_hi:[0,1]
	v_pk_mul_f32 v[26:27], v[44:45], v[26:27] op_sel_hi:[0,1]
	v_pk_mul_f32 v[24:25], v[124:125], v[24:25]
	v_pk_mul_f32 v[26:27], v[126:127], v[26:27]
	v_pk_add_f32 v[190:191], v[190:191], 1.0 op_sel_hi:[1,0]
	v_pk_add_f32 v[188:189], v[188:189], 1.0 op_sel_hi:[1,0]
	v_pk_fma_f32 v[26:27], v[190:191], v[26:27], v[158:159]
	v_pk_fma_f32 v[24:25], v[188:189], v[24:25], v[156:157]
	s_nop 0
	v_cvt_pk_bf16_f32 v24, v24, v25
	v_cvt_pk_bf16_f32 v25, v26, v27
	global_store_dwordx2 v[84:85], v[24:25], off offset:2560
	v_pk_mul_f32 v[16:17], v[44:45], v[16:17] op_sel_hi:[0,1]
	v_pk_mul_f32 v[18:19], v[44:45], v[18:19] op_sel_hi:[0,1]
	v_pk_mul_f32 v[16:17], v[128:129], v[16:17]
	v_pk_mul_f32 v[18:19], v[130:131], v[18:19]
	v_pk_add_f32 v[202:203], v[202:203], 1.0 op_sel_hi:[1,0]
	v_pk_add_f32 v[200:201], v[200:201], 1.0 op_sel_hi:[1,0]
	v_pk_fma_f32 v[18:19], v[202:203], v[18:19], v[162:163]
	v_pk_fma_f32 v[16:17], v[200:201], v[16:17], v[160:161]
	s_nop 0
	v_cvt_pk_bf16_f32 v16, v16, v17
	v_cvt_pk_bf16_f32 v17, v18, v19
	global_store_dwordx2 v[84:85], v[16:17], off offset:3072
	v_pk_mul_f32 v[20:21], v[44:45], v[20:21] op_sel_hi:[0,1]
	v_pk_mul_f32 v[22:23], v[44:45], v[22:23] op_sel_hi:[0,1]
	v_pk_mul_f32 v[20:21], v[132:133], v[20:21]
	v_pk_mul_f32 v[22:23], v[134:135], v[22:23]
	v_pk_add_f32 v[206:207], v[206:207], 1.0 op_sel_hi:[1,0]
	v_pk_add_f32 v[204:205], v[204:205], 1.0 op_sel_hi:[1,0]
	v_pk_fma_f32 v[22:23], v[206:207], v[22:23], v[166:167]
	v_pk_fma_f32 v[20:21], v[204:205], v[20:21], v[164:165]
	s_nop 0
	v_cvt_pk_bf16_f32 v20, v20, v21
	v_cvt_pk_bf16_f32 v21, v22, v23
	global_store_dwordx2 v[84:85], v[20:21], off offset:3584
	s_cbranch_scc1 .LBB0_128

; #define LAS __attribute__((address_space(3)))
; __device__ __forceinline__ void lru_pass3_item(const float* __restrict__ LA, const float* __restrict__ LU, const float* __restrict__ AGG, const bf16_t* __restrict__ GP, bf16_t* __restrict__ O, int item, LAS unsigned char* lds) {
;     ...
;     const int cg = item & 7, bc = item >> 3, c = bc % NCHUNK, b = bc / NCHUNK, row0 = chunk_row0(b, c), ch0 = cg * 128;
;     LAS unsigned* S = (LAS unsigned*)lds;
;     LAS float* CX = (LAS float*)(lds + 65536);
;     {
;         u32x4 tv[8];
; #pragma unroll
;         for (int p = 0; p < 8; ++p) { const int e = p * 512 + tid, arr = e >> 11, rem = e & 2047, tok = rem >> 5, c4 = rem & 31;
;             tv[p] = *(const u32x4*)((const unsigned*)LA + ((size_t)arr * MROWS + row0 + tok) * 1024 + ch0 + c4 * 4); }
; #pragma unroll
;         for (int p = 0; p < 8; ++p) { const int e = p * 512 + tid, arr = e >> 11, rem = e & 2047, tok = rem >> 5, c4 = rem & 31;
;             *(LAS u32x4*)(S + (arr * 64 + tok) * 128 + c4 * 4) = tv[p]; }
.LBB0_693:
	s_lshl_b32 s2, s25, 7
	v_add_u32_e32 v22, 0x200, v25
	s_and_b32 s28, s2, 0x380
	s_ashr_i32 s13, s12, 31
	v_lshlrev_b32_e32 v0, 2, v25
	v_bfe_u32 v38, v25, 5, 6
	v_mov_b32_e32 v39, v195
	v_ashrrev_i32_e32 v2, 11, v22
	s_lshl_b32 s2, s28, 2
	v_and_b32_e32 v23, 0x7c, v0
	v_ashrrev_i32_e32 v0, 11, v25
	v_lshl_add_u64 v[16:17], s[12:13], 0, v[38:39]
	v_bfe_u32 v39, v22, 5, 6
	v_mul_hi_i32_i24_e32 v3, 0x4400, v2
	v_mul_i32_i24_e32 v2, 0x4400, v2
	s_add_u32 s2, s26, s2
	v_mul_hi_i32_i24_e32 v1, 0x4400, v0
	v_mul_i32_i24_e32 v0, 0x4400, v0
	v_or_b32_e32 v2, v2, v39
	v_add_u32_e32 v44, 0x800, v25
	s_addc_u32 s3, s27, 0
	v_lshlrev_b32_e32 v194, 2, v23
	v_lshl_add_u64 v[0:1], v[16:17], 0, v[0:1]
	v_lshl_add_u64 v[2:3], v[2:3], 0, s[12:13]
	v_add_u32_e32 v40, 0x400, v25
	v_add_u32_e32 v42, 0x600, v25
	v_ashrrev_i32_e32 v18, 11, v44
	v_lshl_add_u64 v[20:21], s[2:3], 0, v[194:195]
	v_lshlrev_b64 v[0:1], 12, v[0:1]
	v_lshlrev_b64 v[2:3], 12, v[2:3]
	v_ashrrev_i32_e32 v8, 11, v40
	v_ashrrev_i32_e32 v10, 11, v42
	v_mul_hi_i32_i24_e32 v19, 0x4400, v18
	v_mul_i32_i24_e32 v18, 0x4400, v18
	v_lshl_add_u64 v[0:1], v[20:21], 0, v[0:1]
	v_lshl_add_u64 v[4:5], v[20:21], 0, v[2:3]
	v_bfe_u32 v41, v40, 5, 6
	v_mul_hi_i32_i24_e32 v9, 0x4400, v8
	v_mul_i32_i24_e32 v8, 0x4400, v8
	v_bfe_u32 v43, v42, 5, 6
	v_mul_hi_i32_i24_e32 v11, 0x4400, v10
	v_mul_i32_i24_e32 v10, 0x4400, v10
	v_lshl_add_u64 v[16:17], v[16:17], 0, v[18:19]
	v_add_u32_e32 v18, 0xa00, v25
	global_load_dwordx4 v[0:3], v[0:1], off nt
	s_nop 0
	global_load_dwordx4 v[4:7], v[4:5], off nt
	v_or_b32_e32 v8, v8, v41
	v_or_b32_e32 v10, v10, v43
	v_ashrrev_i32_e32 v24, 11, v18
	v_lshl_add_u64 v[8:9], v[8:9], 0, s[12:13]
	v_lshl_add_u64 v[10:11], v[10:11], 0, s[12:13]
	v_lshrrev_b32_e32 v45, 5, v18
	v_mul_hi_i32_i24_e32 v19, 0x4400, v24
	v_mul_i32_i24_e32 v18, 0x4400, v24
	v_add_u32_e32 v24, 0xc00, v25
	v_lshlrev_b64 v[8:9], 12, v[8:9]
	v_lshlrev_b64 v[10:11], 12, v[10:11]
	v_ashrrev_i32_e32 v30, 11, v24
	v_lshl_add_u64 v[8:9], v[20:21], 0, v[8:9]
	v_lshl_add_u64 v[12:13], v[20:21], 0, v[10:11]
	v_lshrrev_b32_e32 v46, 5, v24
	v_mul_i32_i24_e32 v24, 0x4400, v30
	global_load_dwordx4 v[8:11], v[8:9], off nt
	s_nop 0
	global_load_dwordx4 v[12:15], v[12:13], off nt
	v_mul_hi_i32_i24_e32 v31, 0x4400, v30
	v_and_or_b32 v30, v46, 63, v24
	v_add_u32_e32 v24, 0xe00, v25
	v_and_or_b32 v18, v45, 63, v18
	v_ashrrev_i32_e32 v34, 11, v24
	v_lshl_add_u64 v[18:19], v[18:19], 0, s[12:13]
	v_lshrrev_b32_e32 v47, 5, v24
	v_mul_i32_i24_e32 v24, 0x4400, v34
	v_lshlrev_b64 v[16:17], 12, v[16:17]
	v_lshlrev_b64 v[18:19], 12, v[18:19]
	v_lshl_add_u64 v[30:31], v[30:31], 0, s[12:13]
	v_mul_hi_i32_i24_e32 v35, 0x4400, v34
	v_and_or_b32 v34, v47, 63, v24
	v_lshl_add_u64 v[16:17], v[20:21], 0, v[16:17]
	v_lshl_add_u64 v[26:27], v[20:21], 0, v[18:19]
	v_lshlrev_b64 v[30:31], 12, v[30:31]
	v_lshl_add_u64 v[34:35], v[34:35], 0, s[12:13]
	global_load_dwordx4 v[16:19], v[16:17], off nt
	s_nop 0
	global_load_dwordx4 v[26:29], v[26:27], off nt
	v_lshl_add_u64 v[30:31], v[20:21], 0, v[30:31]
	v_lshlrev_b64 v[34:35], 12, v[34:35]
	global_load_dwordx4 v[30:33], v[30:31], off nt
	v_lshl_add_u64 v[20:21], v[20:21], 0, v[34:35]
	global_load_dwordx4 v[34:37], v[20:21], off nt
	v_ashrrev_i32_e32 v24, 5, v25
	s_mov_b32 s2, 0x7fffc0
	v_add_u32_e32 v48, 0, v194
	v_and_or_b32 v20, v24, s2, v38
	v_lshl_add_u32 v20, v20, 9, v48
	v_ashrrev_i32_e32 v22, 5, v22
	v_ashrrev_i32_e32 v21, 5, v40
	s_waitcnt vmcnt(7)
	ds_write_b128 v20, v[0:3]
	v_and_or_b32 v0, v22, s2, v39
	v_lshl_add_u32 v0, v0, 9, v48
	s_waitcnt vmcnt(6)
	ds_write_b128 v0, v[4:7]
	v_and_or_b32 v0, v21, s2, v41
	v_lshl_add_u32 v0, v0, 9, v48
	v_ashrrev_i32_e32 v20, 5, v42
	s_waitcnt vmcnt(5)
	ds_write_b128 v0, v[8:11]
	v_and_or_b32 v0, v20, s2, v43
	v_lshl_add_u32 v0, v0, 9, v48
	s_waitcnt vmcnt(4)
	ds_write_b128 v0, v[12:15]
	v_lshrrev_b32_e32 v0, 5, v44
	v_and_or_b32 v0, v0, s2, v38
	v_lshl_add_u32 v0, v0, 9, v48
	s_waitcnt vmcnt(3)
	ds_write_b128 v0, v[16:19]
	v_lshl_add_u32 v0, v45, 9, v48
	s_waitcnt vmcnt(2)
	ds_write_b128 v0, v[26:29]
	v_lshl_add_u32 v0, v46, 9, v48
	s_waitcnt vmcnt(1)
	ds_write_b128 v0, v[30:33]
	v_lshl_add_u32 v0, v47, 9, v48
	s_waitcnt vmcnt(0)
	ds_write_b128 v0, v[34:37]
	v_bfe_u32 v26, v25, 7, 1
	v_and_b32_e32 v0, 0x80, v25
	v_cmp_eq_u32_e64 s[2:3], 0, v26
	v_cmp_ne_u32_e64 s[4:5], 0, v0
	v_mov_b32_e32 v0, s21
	s_and_saveexec_b64 s[16:17], s[4:5]
	s_cbranch_execz .LBB0_699
	s_mov_b64 s[18:19], -1
	s_and_b64 vcc, exec, s[0:1]
	s_cbranch_vccz .LBB0_696
	s_sub_i32 s0, 0x47, s21
	s_mov_b64 s[18:19], 0

;     __device__ __forceinline__ void operator()(const AccT& acc, const pg8::Unit& u, int wr, int wc, int fr, int fq) const {
;     ...
;             u32x4 gw8[8], pw8[8];
; #pragma unroll
;             for (int i = 0; i < 8; ++i) { const int row = row0 + ai * 128 + (i >> 1) * 16, col0 = pn * 256 + (i & 1) * 128 + wc * 32 + 8 * fq;
;                 gw8[i] = *(const u32x4*)(mg + (size_t)row * NMG + z * 2048 + col0);
;                 pw8[i] = (z > 0) ? *(const u32x4*)(merged + (size_t)row * 2048 + col0) : (u32x4){0u, 0u, 0u, 0u}; }
.LBB0_834:
	v_mov_b32_e32 v128, v231
	s_lshl_b32 s4, s72, 8
	s_add_i32 s4, s4, s55
	v_and_or_b32 v210, v128, 15, s4
	s_lshl_b32 s4, s28, 8
	v_ashrrev_i32_e32 v128, 1, v128
	v_and_b32_e32 v128, -8, v128
	s_or_b32 s4, s4, s56
	v_add_u32_e32 v208, s4, v128
	s_lshl_b32 s4, s59, 11
	s_ashr_i32 s5, s4, 31
	s_cmp_gt_i32 s59, 0
	s_cselect_b64 s[30:31], -1, 0
	s_lshl_b64 s[4:5], s[4:5], 1
	s_add_u32 s28, s53, s4
	s_addc_u32 s29, s54, s5
	v_mov_b64_e32 v[128:129], s[28:29]
	s_movk_i32 s64, 0x3000
	v_mad_i64_i32 v[128:129], s[4:5], v210, s64, v[128:129]
	v_ashrrev_i32_e32 v209, 31, v208
	v_lshl_add_u64 v[128:129], v[208:209], 1, v[128:129]
	global_load_dwordx4 v[186:189], v[128:129], off nt
	v_ashrrev_i32_e32 v211, 31, v210
	v_lshlrev_b64 v[130:131], 12, v[210:211]
	s_cmp_lt_i32 s59, 1
	v_lshl_add_u64 v[218:219], s[0:1], 0, v[130:131]
	s_cbranch_scc1 .LBB0_836
	v_lshl_add_u64 v[130:131], v[208:209], 1, v[218:219]
	global_load_dwordx4 v[190:193], v[130:131], off
	s_branch .LBB0_837

; __device__ __forceinline__ float bflo(unsigned u) { return __uint_as_float(u << 16); }
; __device__ __forceinline__ float bfhi(unsigned u) { return __uint_as_float(u & 0xffff0000u); }
; __device__ __forceinline__ u32x4 pack8(f32x4 a, f32x4 b) { u32x4 w; w.x = cvt_pk(a[0], a[1]); w.y = cvt_pk(a[2], a[3]); w.z = cvt_pk(b[0], b[1]); w.w = cvt_pk(b[2], b[3]); return w; }
; #define EPI_FENCE(a, b) asm volatile("" : "+v"(a), "+v"(b) :: "memory")
;     __device__ __forceinline__ void operator()(const AccT& acc, const pg8::Unit& u, int wr, int wc, int fr, int fq) const {
;     ...
;             for (int i = 0; i < 8; ++i) { const int row = row0 + ai * 128 + (i >> 1) * 16, col0 = pn * 256 + (i & 1) * 128 + wc * 32 + 8 * fq;
;                 gw8[i] = *(const u32x4*)(mg + (size_t)row * NMG + z * 2048 + col0);
;                 pw8[i] = (z > 0) ? *(const u32x4*)(merged + (size_t)row * 2048 + col0) : (u32x4){0u, 0u, 0u, 0u}; }
; #pragma unroll
;             for (int i = 0; i < 8; ++i) { const int m = i >> 1, bj = i & 1; const int row = row0 + ai * 128 + m * 16, col0 = pn * 256 + bj * 128 + wc * 32 + 8 * fq;
;                 f32x4 v0 = acc[ai][bj][m][0], v1 = acc[ai][bj][m][1]; EPI_FENCE(v0, v1);
;                 const u32x4 gw = gw8[i], pw = pw8[i];
;                 v0[0] = v0[0] * bflo(gw.x) + bflo(pw.x); v0[1] = v0[1] * bfhi(gw.x) + bfhi(pw.x); v0[2] = v0[2] * bflo(gw.y) + bflo(pw.y); v0[3] = v0[3] * bfhi(gw.y) + bfhi(pw.y);
;                 v1[0] = v1[0] * bflo(gw.z) + bflo(pw.z); v1[1] = v1[1] * bfhi(gw.z) + bfhi(pw.z); v1[2] = v1[2] * bflo(gw.w) + bflo(pw.w); v1[3] = v1[3] * bfhi(gw.w) + bfhi(pw.w);
;                 *(u32x4*)(merged + (size_t)row * 2048 + col0) = pack8(v0, v1); }
.LBB0_837:
	global_load_dwordx4 v[178:181], v[128:129], off offset:256 nt
	v_cndmask_b32_e64 v128, 0, 1, s[30:31]
	v_mov_b32_e32 v162, 0
	v_cmp_ne_u32_e64 s[4:5], 1, v128
	s_andn2_b64 vcc, exec, s[30:31]
	v_mov_b32_e32 v182, 0
	v_mov_b32_e32 v183, 0
	v_mov_b32_e32 v184, 0
	v_mov_b32_e32 v185, 0
	s_movk_i32 s65, 0x7e0
	s_movk_i32 s66, 0xc00
	s_cbranch_vccnz .LBB0_839
	v_lshl_add_u64 v[128:129], v[208:209], 1, v[218:219]
	global_load_dwordx4 v[182:185], v[128:129], off offset:256
.LBB0_839:
	v_or_b32_e32 v130, 16, v210
	v_mov_b64_e32 v[128:129], s[28:29]
	v_mad_i64_i32 v[128:129], s[30:31], v130, s64, v[128:129]
	v_lshl_add_u64 v[128:129], v[208:209], 1, v[128:129]
	global_load_dwordx4 v[174:177], v[128:129], off nt
	v_ashrrev_i32_e32 v131, 31, v130
	v_lshlrev_b64 v[130:131], 12, v[130:131]
	s_and_b64 vcc, exec, s[4:5]
	v_lshl_add_u64 v[216:217], s[0:1], 0, v[130:131]
	v_mov_b32_e32 v163, 0
	v_mov_b32_e32 v164, 0
	v_mov_b32_e32 v165, 0
	s_cbranch_vccnz .LBB0_841
	v_lshl_add_u64 v[130:131], v[208:209], 1, v[216:217]
	global_load_dwordx4 v[162:165], v[130:131], off
.LBB0_841:
	global_load_dwordx4 v[170:173], v[128:129], off offset:256 nt
	v_mov_b32_e32 v146, 0
	s_and_b64 vcc, exec, s[4:5]
	v_mov_b32_e32 v166, 0
	v_mov_b32_e32 v167, 0
	v_mov_b32_e32 v168, 0
	v_mov_b32_e32 v169, 0
	s_cbranch_vccnz .LBB0_843
	v_lshl_add_u64 v[128:129], v[208:209], 1, v[216:217]
	global_load_dwordx4 v[166:169], v[128:129], off offset:256
.LBB0_843:
	v_or_b32_e32 v130, 32, v210
	v_mov_b64_e32 v[128:129], s[28:29]
	v_mad_i64_i32 v[128:129], s[30:31], v130, s64, v[128:129]
	v_lshl_add_u64 v[128:129], v[208:209], 1, v[128:129]
	global_load_dwordx4 v[158:161], v[128:129], off nt
	v_ashrrev_i32_e32 v131, 31, v130
	v_lshlrev_b64 v[130:131], 12, v[130:131]
	s_and_b64 vcc, exec, s[4:5]
	v_lshl_add_u64 v[214:215], s[0:1], 0, v[130:131]
	v_mov_b32_e32 v147, 0
	v_mov_b32_e32 v148, 0
	v_mov_b32_e32 v149, 0
	s_cbranch_vccnz .LBB0_845
	v_lshl_add_u64 v[130:131], v[208:209], 1, v[214:215]
	global_load_dwordx4 v[146:149], v[130:131], off
.LBB0_845:
	global_load_dwordx4 v[154:157], v[128:129], off offset:256 nt
	v_mov_b32_e32 v138, 0
	s_and_b64 vcc, exec, s[4:5]
	v_mov_b32_e32 v150, 0
	v_mov_b32_e32 v151, 0
	v_mov_b32_e32 v152, 0
	v_mov_b32_e32 v153, 0
	s_cbranch_vccnz .LBB0_847
	v_lshl_add_u64 v[128:129], v[208:209], 1, v[214:215]
	global_load_dwordx4 v[150:153], v[128:129], off offset:256
.LBB0_847:
	v_or_b32_e32 v130, 48, v210
	v_mov_b64_e32 v[128:129], s[28:29]
	v_mad_i64_i32 v[128:129], s[30:31], v130, s64, v[128:129]
	v_lshl_add_u64 v[128:129], v[208:209], 1, v[128:129]
	global_load_dwordx4 v[142:145], v[128:129], off nt
	v_ashrrev_i32_e32 v131, 31, v130
	v_lshlrev_b64 v[130:131], 12, v[130:131]
	v_lshl_add_u64 v[212:213], s[0:1], 0, v[130:131]
	s_and_b64 vcc, exec, s[4:5]
	v_lshl_add_u64 v[220:221], v[208:209], 1, v[212:213]
	v_mov_b32_e32 v139, 0
	v_mov_b32_e32 v140, 0
	v_mov_b32_e32 v141, 0
	s_cbranch_vccnz .LBB0_849
	global_load_dwordx4 v[138:141], v[220:221], off
.LBB0_849:
	global_load_dwordx4 v[130:133], v[128:129], off offset:256 nt
	v_mov_b32_e32 v128, 0
	s_and_b64 vcc, exec, s[4:5]
	v_mov_b32_e32 v134, 0
	v_mov_b32_e32 v135, 0
	v_mov_b32_e32 v136, 0
	v_mov_b32_e32 v137, 0
	s_cbranch_vccnz .LBB0_851
	global_load_dwordx4 v[134:137], v[220:221], off offset:256
.LBB0_851:
	s_waitcnt vmcnt(0)
	v_lshlrev_b32_e32 v220, 16, v186
	v_and_b32_e32 v221, 0xffff0000, v186
	v_lshlrev_b32_e32 v222, 16, v190
	v_and_b32_e32 v223, 0xffff0000, v190
	v_lshlrev_b32_e32 v186, 16, v187
	v_and_b32_e32 v187, 0xffff0000, v187
	v_lshlrev_b32_e32 v190, 16, v191
	v_and_b32_e32 v191, 0xffff0000, v191
	v_pk_fma_f32 v[126:127], v[126:127], v[186:187], v[190:191]
	v_lshlrev_b32_e32 v186, 16, v188
	v_and_b32_e32 v187, 0xffff0000, v188
	v_lshlrev_b32_e32 v190, 16, v192
	v_and_b32_e32 v191, 0xffff0000, v192
	v_pk_fma_f32 v[186:187], v[120:121], v[186:187], v[190:191]
	v_lshlrev_b32_e32 v120, 16, v189
	v_and_b32_e32 v121, 0xffff0000, v189
	v_lshlrev_b32_e32 v188, 16, v193
	v_and_b32_e32 v189, 0xffff0000, v193
	v_pk_fma_f32 v[124:125], v[124:125], v[220:221], v[222:223]
	v_pk_fma_f32 v[188:189], v[122:123], v[120:121], v[188:189]
	v_cvt_pk_bf16_f32 v121, v126, v127
	v_lshlrev_b64 v[126:127], 1, v[208:209]
	v_cvt_pk_bf16_f32 v120, v124, v125
	v_cvt_pk_bf16_f32 v122, v186, v187
	v_cvt_pk_bf16_f32 v123, v188, v189
	v_lshl_add_u64 v[124:125], v[218:219], 0, v[126:127]
	global_store_dwordx4 v[124:125], v[120:123], off
	s_and_b64 vcc, exec, s[4:5]
	v_mov_b32_e32 v129, 0
	v_lshlrev_b32_e32 v120, 16, v178
	v_and_b32_e32 v121, 0xffff0000, v178
	v_lshlrev_b32_e32 v122, 16, v182
	v_and_b32_e32 v123, 0xffff0000, v182
	v_pk_fma_f32 v[116:117], v[116:117], v[120:121], v[122:123]
	v_lshlrev_b32_e32 v120, 16, v179
	v_and_b32_e32 v121, 0xffff0000, v179
	v_lshlrev_b32_e32 v122, 16, v183
	v_and_b32_e32 v123, 0xffff0000, v183
	v_pk_fma_f32 v[118:119], v[118:119], v[120:121], v[122:123]
	v_lshlrev_b32_e32 v120, 16, v180
	v_and_b32_e32 v121, 0xffff0000, v180
	v_lshlrev_b32_e32 v122, 16, v184
	v_and_b32_e32 v123, 0xffff0000, v184
	v_pk_fma_f32 v[120:121], v[112:113], v[120:121], v[122:123]
	v_lshlrev_b32_e32 v112, 16, v181
	v_and_b32_e32 v113, 0xffff0000, v181
	v_lshlrev_b32_e32 v122, 16, v185
	v_and_b32_e32 v123, 0xffff0000, v185
	v_pk_fma_f32 v[122:123], v[114:115], v[112:113], v[122:123]
	v_cvt_pk_bf16_f32 v112, v116, v117
	v_cvt_pk_bf16_f32 v113, v118, v119
	v_cvt_pk_bf16_f32 v114, v120, v121
	v_cvt_pk_bf16_f32 v115, v122, v123
	global_store_dwordx4 v[124:125], v[112:115], off offset:256
	s_nop 1
	v_lshlrev_b32_e32 v112, 16, v174
	v_and_b32_e32 v113, 0xffff0000, v174
	v_lshlrev_b32_e32 v114, 16, v162
; __device__ __forceinline__ float bflo(unsigned u) { return __uint_as_float(u << 16); }
; __device__ __forceinline__ float bfhi(unsigned u) { return __uint_as_float(u & 0xffff0000u); }
; __device__ __forceinline__ u32x4 pack8(f32x4 a, f32x4 b) { u32x4 w; w.x = cvt_pk(a[0], a[1]); w.y = cvt_pk(a[2], a[3]); w.z = cvt_pk(b[0], b[1]); w.w = cvt_pk(b[2], b[3]); return w; }
; #define EPI_FENCE(a, b) asm volatile("" : "+v"(a), "+v"(b) :: "memory")
;     __device__ __forceinline__ void operator()(const AccT& acc, const pg8::Unit& u, int wr, int wc, int fr, int fq) const {
;     ...
;             u32x4 gw8[8], pw8[8];
; #pragma unroll
;             for (int i = 0; i < 8; ++i) { const int row = row0 + ai * 128 + (i >> 1) * 16, col0 = pn * 256 + (i & 1) * 128 + wc * 32 + 8 * fq;
;                 gw8[i] = *(const u32x4*)(mg + (size_t)row * NMG + z * 2048 + col0);
;                 pw8[i] = (z > 0) ? *(const u32x4*)(merged + (size_t)row * 2048 + col0) : (u32x4){0u, 0u, 0u, 0u}; }
; #pragma unroll
;             for (int i = 0; i < 8; ++i) { const int m = i >> 1, bj = i & 1; const int row = row0 + ai * 128 + m * 16, col0 = pn * 256 + bj * 128 + wc * 32 + 8 * fq;
;                 f32x4 v0 = acc[ai][bj][m][0], v1 = acc[ai][bj][m][1]; EPI_FENCE(v0, v1);
;                 const u32x4 gw = gw8[i], pw = pw8[i];
;                 v0[0] = v0[0] * bflo(gw.x) + bflo(pw.x); v0[1] = v0[1] * bfhi(gw.x) + bfhi(pw.x); v0[2] = v0[2] * bflo(gw.y) + bflo(pw.y); v0[3] = v0[3] * bfhi(gw.y) + bfhi(pw.y);
;                 v1[0] = v1[0] * bflo(gw.z) + bflo(pw.z); v1[1] = v1[1] * bfhi(gw.z) + bfhi(pw.z); v1[2] = v1[2] * bflo(gw.w) + bflo(pw.w); v1[3] = v1[3] * bfhi(gw.w) + bfhi(pw.w);
;                 *(u32x4*)(merged + (size_t)row * 2048 + col0) = pack8(v0, v1); }
	v_and_b32_e32 v115, 0xffff0000, v162
	v_pk_fma_f32 v[108:109], v[108:109], v[112:113], v[114:115]
	v_lshlrev_b32_e32 v112, 16, v175
	v_and_b32_e32 v113, 0xffff0000, v175
	v_lshlrev_b32_e32 v114, 16, v163
	v_and_b32_e32 v115, 0xffff0000, v163
	v_pk_fma_f32 v[110:111], v[110:111], v[112:113], v[114:115]
	v_lshlrev_b32_e32 v112, 16, v176
	v_and_b32_e32 v113, 0xffff0000, v176
	v_lshlrev_b32_e32 v114, 16, v164
	v_and_b32_e32 v115, 0xffff0000, v164
	v_pk_fma_f32 v[112:113], v[104:105], v[112:113], v[114:115]
	v_lshlrev_b32_e32 v104, 16, v177
	v_and_b32_e32 v105, 0xffff0000, v177
	v_lshlrev_b32_e32 v114, 16, v165
	v_and_b32_e32 v115, 0xffff0000, v165
	v_pk_fma_f32 v[114:115], v[106:107], v[104:105], v[114:115]
	v_cvt_pk_bf16_f32 v104, v108, v109
	v_cvt_pk_bf16_f32 v105, v110, v111
	v_cvt_pk_bf16_f32 v106, v112, v113
	v_cvt_pk_bf16_f32 v107, v114, v115
	v_lshl_add_u64 v[108:109], v[216:217], 0, v[126:127]
	global_store_dwordx4 v[108:109], v[104:107], off
	s_nop 1
	v_lshlrev_b32_e32 v104, 16, v170
	v_and_b32_e32 v105, 0xffff0000, v170
	v_lshlrev_b32_e32 v106, 16, v166
	v_and_b32_e32 v107, 0xffff0000, v166
	v_pk_fma_f32 v[100:101], v[100:101], v[104:105], v[106:107]
	v_lshlrev_b32_e32 v104, 16, v171
	v_and_b32_e32 v105, 0xffff0000, v171
	v_lshlrev_b32_e32 v106, 16, v167
	v_and_b32_e32 v107, 0xffff0000, v167
	v_pk_fma_f32 v[102:103], v[102:103], v[104:105], v[106:107]
	v_lshlrev_b32_e32 v104, 16, v172
	v_and_b32_e32 v105, 0xffff0000, v172
	v_lshlrev_b32_e32 v106, 16, v168
	v_and_b32_e32 v107, 0xffff0000, v168
	v_pk_fma_f32 v[104:105], v[96:97], v[104:105], v[106:107]
	v_lshlrev_b32_e32 v96, 16, v173
	v_and_b32_e32 v97, 0xffff0000, v173
	v_lshlrev_b32_e32 v106, 16, v169
	v_and_b32_e32 v107, 0xffff0000, v169
	v_pk_fma_f32 v[106:107], v[98:99], v[96:97], v[106:107]
	v_cvt_pk_bf16_f32 v96, v100, v101
	v_cvt_pk_bf16_f32 v97, v102, v103
	v_cvt_pk_bf16_f32 v98, v104, v105
	v_cvt_pk_bf16_f32 v99, v106, v107
	global_store_dwordx4 v[108:109], v[96:99], off offset:256
	s_nop 1
	v_lshlrev_b32_e32 v96, 16, v158
	v_and_b32_e32 v97, 0xffff0000, v158
	v_lshlrev_b32_e32 v98, 16, v146
	v_and_b32_e32 v99, 0xffff0000, v146
	v_pk_fma_f32 v[92:93], v[92:93], v[96:97], v[98:99]
	v_lshlrev_b32_e32 v96, 16, v159
	v_and_b32_e32 v97, 0xffff0000, v159
	v_lshlrev_b32_e32 v98, 16, v147
	v_and_b32_e32 v99, 0xffff0000, v147
	v_pk_fma_f32 v[94:95], v[94:95], v[96:97], v[98:99]
	v_lshlrev_b32_e32 v96, 16, v160
	v_and_b32_e32 v97, 0xffff0000, v160
	v_lshlrev_b32_e32 v98, 16, v148
	v_and_b32_e32 v99, 0xffff0000, v148
	v_pk_fma_f32 v[96:97], v[88:89], v[96:97], v[98:99]
	v_lshlrev_b32_e32 v88, 16, v161
	v_and_b32_e32 v89, 0xffff0000, v161
	v_lshlrev_b32_e32 v98, 16, v149
	v_and_b32_e32 v99, 0xffff0000, v149
	v_pk_fma_f32 v[98:99], v[90:91], v[88:89], v[98:99]
	v_cvt_pk_bf16_f32 v88, v92, v93
	v_cvt_pk_bf16_f32 v89, v94, v95
	v_cvt_pk_bf16_f32 v90, v96, v97
	v_cvt_pk_bf16_f32 v91, v98, v99
	v_lshl_add_u64 v[92:93], v[214:215], 0, v[126:127]
	global_store_dwordx4 v[92:93], v[88:91], off
	s_nop 1
	v_lshlrev_b32_e32 v88, 16, v154
	v_and_b32_e32 v89, 0xffff0000, v154
	v_lshlrev_b32_e32 v90, 16, v150
	v_and_b32_e32 v91, 0xffff0000, v150
	v_pk_fma_f32 v[84:85], v[84:85], v[88:89], v[90:91]
	v_lshlrev_b32_e32 v88, 16, v155
	v_and_b32_e32 v89, 0xffff0000, v155
	v_lshlrev_b32_e32 v90, 16, v151
	v_and_b32_e32 v91, 0xffff0000, v151
	v_pk_fma_f32 v[86:87], v[86:87], v[88:89], v[90:91]
	v_lshlrev_b32_e32 v88, 16, v156
	v_and_b32_e32 v89, 0xffff0000, v156
	v_lshlrev_b32_e32 v90, 16, v152
	v_and_b32_e32 v91, 0xffff0000, v152
	v_pk_fma_f32 v[88:89], v[80:81], v[88:89], v[90:91]
	v_lshlrev_b32_e32 v80, 16, v157
	v_and_b32_e32 v81, 0xffff0000, v157
	v_lshlrev_b32_e32 v90, 16, v153
	v_and_b32_e32 v91, 0xffff0000, v153
	v_pk_fma_f32 v[90:91], v[82:83], v[80:81], v[90:91]
	v_cvt_pk_bf16_f32 v80, v84, v85
	v_cvt_pk_bf16_f32 v81, v86, v87
	v_cvt_pk_bf16_f32 v82, v88, v89
	v_cvt_pk_bf16_f32 v83, v90, v91
	global_store_dwordx4 v[92:93], v[80:83], off offset:256
	s_nop 1
	v_lshlrev_b32_e32 v80, 16, v142
	v_and_b32_e32 v81, 0xffff0000, v142
	v_lshlrev_b32_e32 v82, 16, v138
	v_and_b32_e32 v83, 0xffff0000, v138
	v_pk_fma_f32 v[76:77], v[76:77], v[80:81], v[82:83]
	v_lshlrev_b32_e32 v80, 16, v143
	v_and_b32_e32 v81, 0xffff0000, v143
	v_lshlrev_b32_e32 v82, 16, v139
	v_and_b32_e32 v83, 0xffff0000, v139
	v_pk_fma_f32 v[78:79], v[78:79], v[80:81], v[82:83]
	v_lshlrev_b32_e32 v80, 16, v144
	v_and_b32_e32 v81, 0xffff0000, v144
	v_lshlrev_b32_e32 v82, 16, v140
	v_and_b32_e32 v83, 0xffff0000, v140
	v_pk_fma_f32 v[80:81], v[72:73], v[80:81], v[82:83]
	v_lshlrev_b32_e32 v72, 16, v145
	v_and_b32_e32 v73, 0xffff0000, v145
	v_lshlrev_b32_e32 v82, 16, v141
	v_and_b32_e32 v83, 0xffff0000, v141
	v_pk_fma_f32 v[82:83], v[74:75], v[72:73], v[82:83]
	v_cvt_pk_bf16_f32 v72, v76, v77
	v_cvt_pk_bf16_f32 v73, v78, v79
	v_cvt_pk_bf16_f32 v74, v80, v81
	v_cvt_pk_bf16_f32 v75, v82, v83
	v_lshl_add_u64 v[76:77], v[212:213], 0, v[126:127]
	global_store_dwordx4 v[76:77], v[72:75], off
	v_lshlrev_b32_e32 v78, 16, v130
	v_and_b32_e32 v79, 0xffff0000, v130
	v_add_u32_e32 v72, 0x80, v210
	v_mov_b64_e32 v[74:75], s[28:29]
	v_mad_i64_i32 v[74:75], s[30:31], v72, s64, v[74:75]
	v_lshl_add_u64 v[74:75], v[74:75], 0, v[126:127]
	global_load_dwordx4 v[120:123], v[74:75], off nt
	v_lshlrev_b32_e32 v80, 16, v134
	v_and_b32_e32 v81, 0xffff0000, v134
	v_pk_fma_f32 v[68:69], v[68:69], v[78:79], v[80:81]
	v_lshlrev_b32_e32 v78, 16, v131
	v_and_b32_e32 v79, 0xffff0000, v131
	v_lshlrev_b32_e32 v80, 16, v135
	v_and_b32_e32 v81, 0xffff0000, v135
	v_pk_fma_f32 v[70:71], v[70:71], v[78:79], v[80:81]
	v_lshlrev_b32_e32 v78, 16, v132
	v_and_b32_e32 v79, 0xffff0000, v132
	v_lshlrev_b32_e32 v80, 16, v136
	v_and_b32_e32 v81, 0xffff0000, v136
	v_pk_fma_f32 v[78:79], v[64:65], v[78:79], v[80:81]
	v_lshlrev_b32_e32 v64, 16, v133
	v_and_b32_e32 v65, 0xffff0000, v133
	v_lshlrev_b32_e32 v80, 16, v137
	v_and_b32_e32 v81, 0xffff0000, v137
	v_pk_fma_f32 v[80:81], v[66:67], v[64:65], v[80:81]
	v_cvt_pk_bf16_f32 v64, v68, v69
	v_cvt_pk_bf16_f32 v65, v70, v71
	v_cvt_pk_bf16_f32 v66, v78, v79
	v_cvt_pk_bf16_f32 v67, v80, v81
	v_ashrrev_i32_e32 v73, 31, v72
	global_store_dwordx4 v[76:77], v[64:67], off offset:256
	v_mov_b32_e32 v130, 0
	v_mov_b32_e32 v131, 0
	v_lshlrev_b64 v[64:65], 12, v[72:73]
	v_lshl_add_u64 v[132:133], s[0:1], 0, v[64:65]
	s_cbranch_vccnz .LBB0_853
	v_lshl_add_u64 v[64:65], v[208:209], 1, v[132:133]
	global_load_dwordx4 v[128:131], v[64:65], off
;     __device__ __forceinline__ void operator()(const AccT& acc, const pg8::Unit& u, int wr, int wc, int fr, int fq) const {
;     ...
;             for (int i = 0; i < 8; ++i) { const int row = row0 + ai * 128 + (i >> 1) * 16, col0 = pn * 256 + (i & 1) * 128 + wc * 32 + 8 * fq;
;                 gw8[i] = *(const u32x4*)(mg + (size_t)row * NMG + z * 2048 + col0);
;                 pw8[i] = (z > 0) ? *(const u32x4*)(merged + (size_t)row * 2048 + col0) : (u32x4){0u, 0u, 0u, 0u}; }
.LBB0_853:
	global_load_dwordx4 v[116:119], v[74:75], off offset:256 nt
	v_mov_b32_e32 v96, 0
	s_and_b64 vcc, exec, s[4:5]
	v_mov_b32_e32 v112, 0
	v_mov_b32_e32 v113, 0
	v_mov_b32_e32 v114, 0
	v_mov_b32_e32 v115, 0
	s_cbranch_vccnz .LBB0_855
	v_lshl_add_u64 v[64:65], v[208:209], 1, v[132:133]
	global_load_dwordx4 v[112:115], v[64:65], off offset:256
.LBB0_855:
	v_or_b32_e32 v64, 16, v72
	v_mov_b64_e32 v[66:67], s[28:29]
	v_mad_i64_i32 v[66:67], s[30:31], v64, s64, v[66:67]
	v_lshl_add_u64 v[66:67], v[208:209], 1, v[66:67]
	global_load_dwordx4 v[108:111], v[66:67], off nt
	v_ashrrev_i32_e32 v65, 31, v64
	v_lshlrev_b64 v[64:65], 12, v[64:65]
	s_and_b64 vcc, exec, s[4:5]
	v_lshl_add_u64 v[64:65], s[0:1], 0, v[64:65]
	v_mov_b32_e32 v97, 0
	v_mov_b32_e32 v98, 0
	v_mov_b32_e32 v99, 0
	s_cbranch_vccnz .LBB0_857
	v_lshl_add_u64 v[68:69], v[208:209], 1, v[64:65]
	global_load_dwordx4 v[96:99], v[68:69], off
.LBB0_857:
	global_load_dwordx4 v[104:107], v[66:67], off offset:256 nt
	v_mov_b32_e32 v80, 0
	s_and_b64 vcc, exec, s[4:5]
	v_mov_b32_e32 v100, 0
	v_mov_b32_e32 v101, 0
	v_mov_b32_e32 v102, 0
	v_mov_b32_e32 v103, 0
	s_cbranch_vccnz .LBB0_859
	v_lshl_add_u64 v[64:65], v[208:209], 1, v[64:65]
	global_load_dwordx4 v[100:103], v[64:65], off offset:256
.LBB0_859:
	v_or_b32_e32 v66, 32, v72
	v_mov_b64_e32 v[64:65], s[28:29]
	v_mad_i64_i32 v[64:65], s[30:31], v66, s64, v[64:65]
	v_lshl_add_u64 v[64:65], v[208:209], 1, v[64:65]
	global_load_dwordx4 v[92:95], v[64:65], off nt
	v_ashrrev_i32_e32 v67, 31, v66
	v_lshlrev_b64 v[66:67], 12, v[66:67]
	s_and_b64 vcc, exec, s[4:5]
	v_lshl_add_u64 v[66:67], s[0:1], 0, v[66:67]
	v_mov_b32_e32 v81, 0
	v_mov_b32_e32 v82, 0
	v_mov_b32_e32 v83, 0
	s_cbranch_vccnz .LBB0_861
	v_lshl_add_u64 v[68:69], v[208:209], 1, v[66:67]
	global_load_dwordx4 v[80:83], v[68:69], off
.LBB0_861:
	global_load_dwordx4 v[88:91], v[64:65], off offset:256 nt
	v_mov_b32_e32 v64, 0
	s_and_b64 vcc, exec, s[4:5]
	v_mov_b32_e32 v84, 0
	v_mov_b32_e32 v85, 0
	v_mov_b32_e32 v86, 0
	v_mov_b32_e32 v87, 0
	s_cbranch_vccnz .LBB0_863
	v_lshl_add_u64 v[66:67], v[208:209], 1, v[66:67]
	global_load_dwordx4 v[84:87], v[66:67], off offset:256
.LBB0_863:
	v_or_b32_e32 v66, 48, v72
	v_mov_b64_e32 v[68:69], s[28:29]
	v_mad_i64_i32 v[68:69], s[28:29], v66, s64, v[68:69]
	v_lshl_add_u64 v[68:69], v[208:209], 1, v[68:69]
	global_load_dwordx4 v[76:79], v[68:69], off nt
	v_ashrrev_i32_e32 v67, 31, v66
	v_lshlrev_b64 v[66:67], 12, v[66:67]
	s_and_b64 vcc, exec, s[4:5]
	v_lshl_add_u64 v[70:71], s[0:1], 0, v[66:67]
	v_mov_b32_e32 v65, 0
	v_mov_b32_e32 v66, 0
	v_mov_b32_e32 v67, 0
	s_cbranch_vccnz .LBB0_865
	v_lshl_add_u64 v[64:65], v[208:209], 1, v[70:71]
	global_load_dwordx4 v[64:67], v[64:65], off
.LBB0_865:
	s_nop 0
	global_load_dwordx4 v[72:75], v[68:69], off offset:256 nt
	s_and_b64 vcc, exec, s[4:5]
	s_cbranch_vccnz .LBB0_867
	v_lshl_add_u64 v[68:69], v[208:209], 1, v[70:71]
	global_load_dwordx4 v[68:71], v[68:69], off offset:256
	s_branch .LBB0_868
